# weight-convert phases: the four row loads of each 64x64 tile are issued together with one wait instead of four serial load-wait-convert rounds
# baseline (speedup 1.0000x reference)
.LBB0_64:
	s_mul_i32 s35, s35, s34
	s_sub_i32 s34, s93, s35
	v_lshl_add_u64 v[0:1], v[6:7], 2, s[86:87]
	s_lshl_b32 s88, s34, 6
	v_cmp_lt_i32_e32 vcc, -1, v6
	v_lshl_add_u64 v[12:13], v[0:1], 0, v[8:9]
	v_mov_b32_e32 v2, 0
	v_mov_b32_e32 v3, 0
	v_mov_b32_e32 v4, 0
	v_mov_b32_e32 v5, 0
	v_mov_b32_e32 v200, 0
	v_mov_b32_e32 v201, 0
	v_mov_b32_e32 v202, 0
	v_mov_b32_e32 v203, 0
	v_mov_b32_e32 v204, 0
	v_mov_b32_e32 v205, 0
	v_mov_b32_e32 v206, 0
	v_mov_b32_e32 v207, 0
	v_mov_b32_e32 v208, 0
	v_mov_b32_e32 v209, 0
	v_mov_b32_e32 v210, 0
	v_mov_b32_e32 v211, 0
	s_and_saveexec_b64 s[86:87], vcc
	s_cbranch_execz .Lcv_x_0
	v_add_u32_e32 v212, s88, v14
	v_ashrrev_i32_e32 v213, 31, v212
	v_mul_lo_u32 v214, s84, v213
	v_mul_lo_u32 v215, s85, v212
	v_mad_u64_u32 v[216:217], s[34:35], s84, v212, 0
	v_add3_u32 v217, v217, v214, v215
	v_lshl_add_u64 v[216:217], v[216:217], 2, v[12:13]
	global_load_dwordx4 v[2:5], v[216:217], off nt
	v_add_u32_e32 v212, s88, v21
	v_ashrrev_i32_e32 v213, 31, v212
	v_mul_lo_u32 v214, s84, v213
	v_mul_lo_u32 v215, s85, v212
	v_mad_u64_u32 v[216:217], s[34:35], s84, v212, 0
	v_add3_u32 v217, v217, v214, v215
	v_lshl_add_u64 v[216:217], v[216:217], 2, v[12:13]
	global_load_dwordx4 v[200:203], v[216:217], off nt
	v_add_u32_e32 v212, s88, v22
	v_ashrrev_i32_e32 v213, 31, v212
	v_mul_lo_u32 v214, s84, v213
	v_mul_lo_u32 v215, s85, v212
	v_mad_u64_u32 v[216:217], s[34:35], s84, v212, 0
	v_add3_u32 v217, v217, v214, v215
	v_lshl_add_u64 v[216:217], v[216:217], 2, v[12:13]
	global_load_dwordx4 v[204:207], v[216:217], off nt
	v_add_u32_e32 v212, s88, v23
	v_ashrrev_i32_e32 v213, 31, v212
	v_mul_lo_u32 v214, s84, v213
	v_mul_lo_u32 v215, s85, v212
	v_mad_u64_u32 v[216:217], s[34:35], s84, v212, 0
	v_add3_u32 v217, v217, v214, v215
	v_lshl_add_u64 v[216:217], v[216:217], 2, v[12:13]
	global_load_dwordx4 v[208:211], v[216:217], off nt
.Lcv_x_0:
	s_or_b64 exec, exec, s[86:87]
	s_waitcnt vmcnt(0)
	v_cvt_f16_f32_e32 v2, v2
	v_cvt_f16_f32_e32 v3, v3
	v_cvt_f16_f32_e32 v4, v4
	v_cvt_f16_f32_e32 v5, v5
	ds_write_b16 v20, v2
	ds_write_b16 v20, v3 offset:144
	ds_write_b16 v20, v4 offset:288
	ds_write_b16 v20, v5 offset:432
	v_cvt_f16_f32_e32 v200, v200
	v_cvt_f16_f32_e32 v201, v201
	v_cvt_f16_f32_e32 v202, v202
	v_cvt_f16_f32_e32 v203, v203
	ds_write_b16 v20, v200 offset:32
	ds_write_b16 v20, v201 offset:176
	ds_write_b16 v20, v202 offset:320
	ds_write_b16 v20, v203 offset:464
	v_cvt_f16_f32_e32 v204, v204
	v_cvt_f16_f32_e32 v205, v205
	v_cvt_f16_f32_e32 v206, v206
	v_cvt_f16_f32_e32 v207, v207
	ds_write_b16 v20, v204 offset:64
	ds_write_b16 v20, v205 offset:208
	ds_write_b16 v20, v206 offset:352
	ds_write_b16 v20, v207 offset:496
	v_mov_b32_e32 v0, v208
	v_mov_b32_e32 v1, v209
	v_mov_b32_e32 v2, v210
	v_mov_b32_e32 v3, v211
	s_branch .LBB0_26

.LBB0_1055:
	s_mul_i32 s35, s35, s34
	s_sub_i32 s34, s69, s35
	v_lshl_add_u64 v[0:1], v[6:7], 2, s[52:53]
	s_lshl_b32 s56, s34, 6
	v_cmp_lt_i32_e32 vcc, -1, v6
	v_lshl_add_u64 v[12:13], v[0:1], 0, v[8:9]
	v_mov_b32_e32 v2, 0
	v_mov_b32_e32 v3, 0
	v_mov_b32_e32 v4, 0
	v_mov_b32_e32 v5, 0
	v_mov_b32_e32 v200, 0
	v_mov_b32_e32 v201, 0
	v_mov_b32_e32 v202, 0
	v_mov_b32_e32 v203, 0
	v_mov_b32_e32 v204, 0
	v_mov_b32_e32 v205, 0
	v_mov_b32_e32 v206, 0
	v_mov_b32_e32 v207, 0
	v_mov_b32_e32 v208, 0
	v_mov_b32_e32 v209, 0
	v_mov_b32_e32 v210, 0
	v_mov_b32_e32 v211, 0
	s_and_saveexec_b64 s[52:53], vcc
	s_cbranch_execz .Lcv_x_1
	v_add_u32_e32 v212, s56, v14
	v_ashrrev_i32_e32 v213, 31, v212
	v_mul_lo_u32 v214, s26, v213
	v_mul_lo_u32 v215, s27, v212
	v_mad_u64_u32 v[216:217], s[34:35], s26, v212, 0
	v_add3_u32 v217, v217, v214, v215
	v_lshl_add_u64 v[216:217], v[216:217], 2, v[12:13]
	global_load_dwordx4 v[2:5], v[216:217], off nt
	v_add_u32_e32 v212, s56, v21
	v_ashrrev_i32_e32 v213, 31, v212
	v_mul_lo_u32 v214, s26, v213
	v_mul_lo_u32 v215, s27, v212
	v_mad_u64_u32 v[216:217], s[34:35], s26, v212, 0
	v_add3_u32 v217, v217, v214, v215
	v_lshl_add_u64 v[216:217], v[216:217], 2, v[12:13]
	global_load_dwordx4 v[200:203], v[216:217], off nt
	v_add_u32_e32 v212, s56, v22
	v_ashrrev_i32_e32 v213, 31, v212
	v_mul_lo_u32 v214, s26, v213
	v_mul_lo_u32 v215, s27, v212
	v_mad_u64_u32 v[216:217], s[34:35], s26, v212, 0
	v_add3_u32 v217, v217, v214, v215
	v_lshl_add_u64 v[216:217], v[216:217], 2, v[12:13]
	global_load_dwordx4 v[204:207], v[216:217], off nt
	v_add_u32_e32 v212, s56, v23
	v_ashrrev_i32_e32 v213, 31, v212
	v_mul_lo_u32 v214, s26, v213
	v_mul_lo_u32 v215, s27, v212
	v_mad_u64_u32 v[216:217], s[34:35], s26, v212, 0
	v_add3_u32 v217, v217, v214, v215
	v_lshl_add_u64 v[216:217], v[216:217], 2, v[12:13]
	global_load_dwordx4 v[208:211], v[216:217], off nt
.Lcv_x_1:
	s_or_b64 exec, exec, s[52:53]
	s_waitcnt vmcnt(0)
	v_cvt_f16_f32_e32 v2, v2
	v_cvt_f16_f32_e32 v3, v3
	v_cvt_f16_f32_e32 v4, v4
	v_cvt_f16_f32_e32 v5, v5
	ds_write_b16 v20, v2
	ds_write_b16 v20, v3 offset:144
	ds_write_b16 v20, v4 offset:288
	ds_write_b16 v20, v5 offset:432
	v_cvt_f16_f32_e32 v200, v200
	v_cvt_f16_f32_e32 v201, v201
	v_cvt_f16_f32_e32 v202, v202
	v_cvt_f16_f32_e32 v203, v203
	ds_write_b16 v20, v200 offset:32
	ds_write_b16 v20, v201 offset:176
	ds_write_b16 v20, v202 offset:320
	ds_write_b16 v20, v203 offset:464
	v_cvt_f16_f32_e32 v204, v204
	v_cvt_f16_f32_e32 v205, v205
	v_cvt_f16_f32_e32 v206, v206
	v_cvt_f16_f32_e32 v207, v207
	ds_write_b16 v20, v204 offset:64
	ds_write_b16 v20, v205 offset:208
	ds_write_b16 v20, v206 offset:352
	ds_write_b16 v20, v207 offset:496
	v_mov_b32_e32 v0, v208
	v_mov_b32_e32 v1, v209
	v_mov_b32_e32 v2, v210
	v_mov_b32_e32 v3, v211
	s_branch .LBB0_1016
